# grid barrier: non-leader workgroups poll the top-level generation word directly, per-XCD generation hop removed
# baseline (speedup 1.0000x reference)
.LBB0_391:
	s_or_b64 exec, exec, s[10:11]
	v_cvt_f32_u32_e32 v4, v2
	s_waitcnt vmcnt(0)
	v_readfirstlane_b32 s2, v3
	v_sub_u32_e32 v3, 0, v2
	v_rcp_iflag_f32_e32 v4, v4
	v_add_u32_e32 v5, s2, v1
	v_mul_f32_e32 v4, 0x4f7ffffe, v4
	v_cvt_u32_f32_e32 v4, v4
	v_mul_lo_u32 v1, v3, v4
	v_mul_hi_u32 v1, v4, v1
	v_add_u32_e32 v1, v4, v1
	v_mul_hi_u32 v1, v5, v1
	v_mul_lo_u32 v3, v1, v2
	v_sub_u32_e32 v3, v5, v3
	v_add_u32_e32 v4, 1, v1
	v_cmp_ge_u32_e32 vcc, v3, v2
	s_nop 1
	v_cndmask_b32_e32 v1, v1, v4, vcc
	v_sub_u32_e32 v4, v3, v2
	v_cndmask_b32_e32 v3, v3, v4, vcc
	v_add_u32_e32 v4, 1, v1
	v_cmp_ge_u32_e32 vcc, v3, v2
	v_add_u32_e32 v3, 1, v5
	s_nop 0
	v_cndmask_b32_e32 v1, v1, v4, vcc
	v_mul_lo_u32 v4, v2, v1
	v_add_u32_e32 v2, v4, v2
	v_cmp_ne_u32_e32 vcc, v3, v2
	s_and_saveexec_b64 s[2:3], vcc
	s_xor_b64 s[8:9], exec, s[2:3]
	s_cbranch_execz .LBB0_405
	s_waitcnt lgkmcnt(0)
	v_mov_b32_e32 v0, 0x4000
	global_load_dword v0, v0, s[86:87] offset:1280 sc1
	s_add_u32 s14, s86, 0x4500
	s_addc_u32 s15, s87, 0
	s_waitcnt vmcnt(0)
	v_cmp_eq_u32_e32 vcc, v0, v1
	s_and_saveexec_b64 s[10:11], vcc
	s_cbranch_execz .LBB0_404
	s_add_u32 s12, s86, 0x1200
	s_addc_u32 s13, s87, 0
	s_mov_b32 s2, 1
	s_mov_b64 s[24:25], 0
	v_mov_b32_e32 v0, 0
	s_branch .LBB0_395

.LBB0_422:
	s_or_b64 exec, exec, s[8:9]
	s_mov_b64 s[8:9], exec
	v_mbcnt_lo_u32_b32 v0, s8, 0
	v_mbcnt_hi_u32_b32 v0, s9, v0
	v_cmp_eq_u32_e32 vcc, 0, v0
	s_waitcnt vmcnt(0)
	buffer_inv sc1
	s_and_saveexec_b64 s[10:11], vcc
	s_cbranch_execz .LBB0_424
	s_bcnt1_i32_b64 s2, s[8:9]
	v_mov_b32_e32 v0, 0x2000
	v_mov_b32_e32 v1, s2
.LBB0_424:
	s_or_b64 exec, exec, s[10:11]
	s_waitcnt vmcnt(0)

.LBB0_660:
	s_or_b64 exec, exec, s[10:11]
	v_cvt_f32_u32_e32 v4, v2
	s_waitcnt vmcnt(0)
	v_readfirstlane_b32 s2, v3
	v_sub_u32_e32 v3, 0, v2
	v_rcp_iflag_f32_e32 v4, v4
	v_add_u32_e32 v5, s2, v1
	v_mul_f32_e32 v4, 0x4f7ffffe, v4
	v_cvt_u32_f32_e32 v4, v4
	v_mul_lo_u32 v1, v3, v4
	v_mul_hi_u32 v1, v4, v1
	v_add_u32_e32 v1, v4, v1
	v_mul_hi_u32 v1, v5, v1
	v_mul_lo_u32 v3, v1, v2
	v_sub_u32_e32 v3, v5, v3
	v_add_u32_e32 v4, 1, v1
	v_cmp_ge_u32_e32 vcc, v3, v2
	s_nop 1
	v_cndmask_b32_e32 v1, v1, v4, vcc
	v_sub_u32_e32 v4, v3, v2
	v_cndmask_b32_e32 v3, v3, v4, vcc
	v_add_u32_e32 v4, 1, v1
	v_cmp_ge_u32_e32 vcc, v3, v2
	v_add_u32_e32 v3, 1, v5
	s_nop 0
	v_cndmask_b32_e32 v1, v1, v4, vcc
	v_mul_lo_u32 v4, v2, v1
	v_add_u32_e32 v2, v4, v2
	v_cmp_ne_u32_e32 vcc, v3, v2
	s_and_saveexec_b64 s[2:3], vcc
	s_xor_b64 s[8:9], exec, s[2:3]
	s_cbranch_execz .LBB0_674
	s_waitcnt lgkmcnt(0)
	v_mov_b32_e32 v0, 0x4000
	global_load_dword v0, v0, s[86:87] offset:1280 sc1
	s_add_u32 s14, s86, 0x4500
	s_addc_u32 s15, s87, 0
	s_waitcnt vmcnt(0)
	v_cmp_eq_u32_e32 vcc, v0, v1
	s_and_saveexec_b64 s[10:11], vcc
	s_cbranch_execz .LBB0_673
	s_add_u32 s12, s86, 0x1200
	s_addc_u32 s13, s87, 0
	s_mov_b32 s2, 1
	s_mov_b64 s[16:17], 0
	v_mov_b32_e32 v0, 0
	s_branch .LBB0_664

.LBB0_691:
	s_or_b64 exec, exec, s[8:9]
	s_mov_b64 s[8:9], exec
	v_mbcnt_lo_u32_b32 v0, s8, 0
	v_mbcnt_hi_u32_b32 v0, s9, v0
	v_cmp_eq_u32_e32 vcc, 0, v0
	s_waitcnt vmcnt(0)
	buffer_inv sc1
	s_and_saveexec_b64 s[10:11], vcc
	s_cbranch_execz .LBB0_693
	s_bcnt1_i32_b64 s2, s[8:9]
	v_mov_b32_e32 v0, 0x2000
	v_mov_b32_e32 v1, s2
.LBB0_693:
	s_or_b64 exec, exec, s[10:11]
	s_waitcnt vmcnt(0)

.LBB0_784:
	s_or_b64 exec, exec, s[8:9]
	s_mov_b64 s[8:9], exec
	v_mbcnt_lo_u32_b32 v0, s8, 0
	v_mbcnt_hi_u32_b32 v0, s9, v0
	v_cmp_eq_u32_e32 vcc, 0, v0
	s_waitcnt vmcnt(0)
	buffer_inv sc1
	s_and_saveexec_b64 s[10:11], vcc
	s_cbranch_execz .LBB0_786
	s_bcnt1_i32_b64 s2, s[8:9]
	v_mov_b32_e32 v0, 0x2000
	v_mov_b32_e32 v1, s2
.LBB0_786:
	s_or_b64 exec, exec, s[10:11]
	s_waitcnt vmcnt(0)

.LBB0_1235:
	s_or_b64 exec, exec, s[8:9]
	s_mov_b64 s[8:9], exec
	v_mbcnt_lo_u32_b32 v0, s8, 0
	v_mbcnt_hi_u32_b32 v0, s9, v0
	v_cmp_eq_u32_e32 vcc, 0, v0
	s_waitcnt vmcnt(0)
	buffer_inv sc1
	s_and_saveexec_b64 s[10:11], vcc
	s_cbranch_execz .LBB0_1237
	s_bcnt1_i32_b64 s2, s[8:9]
	v_mov_b32_e32 v0, 0x2000
	v_mov_b32_e32 v1, s2
.LBB0_1237:
	s_or_b64 exec, exec, s[10:11]
	s_waitcnt vmcnt(0)

.LBB0_1339:
	s_or_b64 exec, exec, s[8:9]
	s_mov_b64 s[8:9], exec
	v_mbcnt_lo_u32_b32 v0, s8, 0
	v_mbcnt_hi_u32_b32 v0, s9, v0
	v_cmp_eq_u32_e32 vcc, 0, v0
	s_waitcnt vmcnt(0)
	buffer_inv sc1
	s_and_saveexec_b64 s[10:11], vcc
	s_cbranch_execz .LBB0_1341
	s_bcnt1_i32_b64 s2, s[8:9]
	v_mov_b32_e32 v0, 0x2000
	v_mov_b32_e32 v1, s2
.LBB0_1341:
	s_or_b64 exec, exec, s[10:11]
	s_waitcnt vmcnt(0)

.LBB0_1443:
	s_or_b64 exec, exec, s[8:9]
	s_mov_b64 s[8:9], exec
	v_mbcnt_lo_u32_b32 v0, s8, 0
	v_mbcnt_hi_u32_b32 v0, s9, v0
	v_cmp_eq_u32_e32 vcc, 0, v0
	s_waitcnt vmcnt(0)
	buffer_inv sc1
	s_and_saveexec_b64 s[10:11], vcc
	s_cbranch_execz .LBB0_1445
	s_bcnt1_i32_b64 s2, s[8:9]
	v_mov_b32_e32 v0, 0x2000
	v_mov_b32_e32 v1, s2
.LBB0_1445:
	s_or_b64 exec, exec, s[10:11]
	s_waitcnt vmcnt(0)

.LBB0_1521:
	s_or_b64 exec, exec, s[8:9]
	s_mov_b64 s[8:9], exec
	v_mbcnt_lo_u32_b32 v0, s8, 0
	v_mbcnt_hi_u32_b32 v0, s9, v0
	v_cmp_eq_u32_e32 vcc, 0, v0
	s_waitcnt vmcnt(0)
	buffer_inv sc1
	s_and_saveexec_b64 s[10:11], vcc
	s_cbranch_execz .LBB0_1523
	s_bcnt1_i32_b64 s2, s[8:9]
	v_mov_b32_e32 v0, 0x2000
	v_mov_b32_e32 v1, s2
.LBB0_1523:
	s_or_b64 exec, exec, s[10:11]
	s_waitcnt vmcnt(0)

.LBB0_1625:
	s_or_b64 exec, exec, s[8:9]
	s_mov_b64 s[8:9], exec
	v_mbcnt_lo_u32_b32 v0, s8, 0
	v_mbcnt_hi_u32_b32 v0, s9, v0
	v_cmp_eq_u32_e32 vcc, 0, v0
	s_waitcnt vmcnt(0)
	buffer_inv sc1
	s_and_saveexec_b64 s[10:11], vcc
	s_cbranch_execz .LBB0_1627
	s_bcnt1_i32_b64 s2, s[8:9]
	v_mov_b32_e32 v0, 0x2000
	v_mov_b32_e32 v1, s2
.LBB0_1627:
	s_or_b64 exec, exec, s[10:11]
	s_waitcnt vmcnt(0)
